# v044 + removed the compiler's conservative mid-loop vmcnt(0) before the V transposed reads (DMA targets the other LDS stage)
# baseline (speedup 1.0000x reference)
; #define ATT_VREAD(dst, q_) do { const LAS char* vp_ = (const LAS char*)vb + (((q_) >> 1) * 32 + 16 * ((q_) & 1)) * VSTR; \
;         _Pragma("unroll") for (int d_ = 0; d_ < 4; ++d_) { dst[d_][0] = vtr(vp_ + voff[d_][0]); dst[d_][1] = vtr(vp_ + 8 * VSTR + voff[d_][1]); } } while (0)
;     ...
;         float mx = fmaxf(s0[0], s1[0]);
; #pragma unroll
;         for (int r = 1; r < 16; ++r) mx = fmaxf(mx, fmaxf(s0[r], s1[r]));
;         mx = fmaxf(mx, __shfl_xor(mx, 32));
;         const bool need = mx > mrun + 8.f;
;         if (__any(need)) { const float mnew = need ? mx : mrun, alpha = __builtin_amdgcn_exp2f(mrun - mnew); mrun = mnew; lrun *= alpha;
; #pragma unroll
;             for (int d = 0; d < 4; ++d)
; #pragma unroll
;                 for (int r = 0; r < 16; ++r) o[d][r] *= alpha; }
;     ...
;             if (wka) { vb = sa + KBUF + vlane; ATT_VREAD(vpre, 0); SM(wa0, wa1, a0, a1, pba);
.LBB0_586:
	v_add_u32_e32 v148, s1, v194
	s_andn2_b64 vcc, exec, s[28:29]
	v_add_u32_e32 v200, v148, v186
	v_add_u32_e32 v201, v148, v187
	v_add_u32_e32 v202, v148, v188
	v_add_u32_e32 v203, v148, v189
	v_add_u32_e32 v204, v148, v190
	v_add_u32_e32 v205, v148, v191
	v_add_u32_e32 v206, v148, v192
	v_add_u32_e32 v207, v148, v193
	s_cbranch_vccnz .LBB0_590
	v_max_f32_e32 v156, v101, v101
	v_max_f32_e32 v157, v69, v69
	v_max_f32_e32 v156, v157, v156
	v_max_f32_e32 v157, v102, v102
	v_max_f32_e32 v158, v70, v70
	v_max_f32_e32 v157, v158, v157
	v_max_f32_e32 v158, v103, v103
	v_max_f32_e32 v159, v71, v71
	v_max3_f32 v156, v68, v100, v156
	v_max_f32_e32 v158, v159, v158
	v_max3_f32 v156, v156, v157, v158
	v_max_f32_e32 v157, v104, v104
	v_max_f32_e32 v158, v72, v72
	v_max_f32_e32 v157, v158, v157
	v_max_f32_e32 v158, v105, v105
	v_max_f32_e32 v159, v73, v73
	v_max_f32_e32 v158, v159, v158
	v_max3_f32 v156, v156, v157, v158
	v_max_f32_e32 v157, v106, v106
	v_max_f32_e32 v158, v74, v74
	v_max_f32_e32 v157, v158, v157
	v_max_f32_e32 v158, v107, v107
	v_max_f32_e32 v159, v75, v75
	v_max_f32_e32 v158, v159, v158
	v_max3_f32 v156, v156, v157, v158
	v_max_f32_e32 v157, v108, v108
	v_max_f32_e32 v158, v76, v76
	v_max_f32_e32 v157, v158, v157
	v_max_f32_e32 v158, v109, v109
	v_max_f32_e32 v159, v77, v77
	v_max_f32_e32 v158, v159, v158
	v_max3_f32 v156, v156, v157, v158
	v_max_f32_e32 v157, v110, v110
	v_max_f32_e32 v158, v78, v78
	v_max_f32_e32 v157, v158, v157
	v_max_f32_e32 v158, v111, v111
	v_max_f32_e32 v159, v79, v79
	v_max_f32_e32 v158, v159, v158
	v_max3_f32 v156, v156, v157, v158
	v_max_f32_e32 v157, v112, v112
	v_max_f32_e32 v158, v80, v80
	v_max_f32_e32 v157, v158, v157
	v_max_f32_e32 v158, v113, v113
	v_max_f32_e32 v159, v81, v81
	v_max_f32_e32 v158, v159, v158
	v_max3_f32 v156, v156, v157, v158
	v_max_f32_e32 v157, v114, v114
	v_max_f32_e32 v158, v82, v82
	v_max_f32_e32 v157, v158, v157
	v_max_f32_e32 v158, v115, v115
	v_max_f32_e32 v159, v83, v83
	v_max_f32_e32 v158, v159, v158
	v_max3_f32 v208, v156, v157, v158
	ds_read_b64_tr_b16 v[152:153], v200 offset:16384
	ds_read_b64_tr_b16 v[154:155], v201 offset:18432
	ds_read_b64_tr_b16 v[148:149], v202 offset:16384
	ds_read_b64_tr_b16 v[150:151], v203 offset:18432
	v_mov_b32_e32 v246, v208
	v_mov_b32_e32 v247, v208
	ds_read_b64_tr_b16 v[160:161], v204 offset:16384
	ds_read_b64_tr_b16 v[162:163], v205 offset:18432
	ds_read_b64_tr_b16 v[156:157], v206 offset:16384
	ds_read_b64_tr_b16 v[158:159], v207 offset:18432
	v_permlane32_swap_b32_e32 v246, v247
	v_max3_f32 v208, v208, v246, v247
	v_add_f32_e32 v209, 0x41000000, v170
	v_cmp_gt_f32_e32 vcc, v208, v209
	s_cbranch_vccz .LBB0_589
	s_nop 0
	v_cndmask_b32_e32 v208, v170, v208, vcc
	v_sub_f32_e32 v170, v170, v208
	v_exp_f32_e32 v170, v170
	s_nop 0
	v_mul_f32_e32 v167, v167, v170
	v_pk_mul_f32 v[66:67], v[66:67], v[170:171] op_sel_hi:[1,0]
	v_pk_mul_f32 v[64:65], v[64:65], v[170:171] op_sel_hi:[1,0]
	v_pk_mul_f32 v[62:63], v[62:63], v[170:171] op_sel_hi:[1,0]
	v_pk_mul_f32 v[60:61], v[60:61], v[170:171] op_sel_hi:[1,0]
	v_pk_mul_f32 v[58:59], v[58:59], v[170:171] op_sel_hi:[1,0]
	v_pk_mul_f32 v[56:57], v[56:57], v[170:171] op_sel_hi:[1,0]
	v_pk_mul_f32 v[54:55], v[54:55], v[170:171] op_sel_hi:[1,0]
	v_pk_mul_f32 v[52:53], v[52:53], v[170:171] op_sel_hi:[1,0]
	v_pk_mul_f32 v[50:51], v[50:51], v[170:171] op_sel_hi:[1,0]
	v_pk_mul_f32 v[48:49], v[48:49], v[170:171] op_sel_hi:[1,0]
	v_pk_mul_f32 v[46:47], v[46:47], v[170:171] op_sel_hi:[1,0]
	v_pk_mul_f32 v[44:45], v[44:45], v[170:171] op_sel_hi:[1,0]
	v_pk_mul_f32 v[42:43], v[42:43], v[170:171] op_sel_hi:[1,0]
	v_pk_mul_f32 v[40:41], v[40:41], v[170:171] op_sel_hi:[1,0]
	v_pk_mul_f32 v[38:39], v[38:39], v[170:171] op_sel_hi:[1,0]
	v_pk_mul_f32 v[36:37], v[36:37], v[170:171] op_sel_hi:[1,0]
	v_pk_mul_f32 v[34:35], v[34:35], v[170:171] op_sel_hi:[1,0]
	v_pk_mul_f32 v[32:33], v[32:33], v[170:171] op_sel_hi:[1,0]
	v_pk_mul_f32 v[30:31], v[30:31], v[170:171] op_sel_hi:[1,0]
	v_pk_mul_f32 v[28:29], v[28:29], v[170:171] op_sel_hi:[1,0]
	v_pk_mul_f32 v[26:27], v[26:27], v[170:171] op_sel_hi:[1,0]
	v_pk_mul_f32 v[24:25], v[24:25], v[170:171] op_sel_hi:[1,0]
	v_pk_mul_f32 v[22:23], v[22:23], v[170:171] op_sel_hi:[1,0]
	v_pk_mul_f32 v[20:21], v[20:21], v[170:171] op_sel_hi:[1,0]
	v_pk_mul_f32 v[18:19], v[18:19], v[170:171] op_sel_hi:[1,0]
	v_pk_mul_f32 v[16:17], v[16:17], v[170:171] op_sel_hi:[1,0]
	v_pk_mul_f32 v[14:15], v[14:15], v[170:171] op_sel_hi:[1,0]
	v_pk_mul_f32 v[12:13], v[12:13], v[170:171] op_sel_hi:[1,0]
	v_pk_mul_f32 v[10:11], v[10:11], v[170:171] op_sel_hi:[1,0]
	v_pk_mul_f32 v[8:9], v[8:9], v[170:171] op_sel_hi:[1,0]
	v_pk_mul_f32 v[6:7], v[6:7], v[170:171] op_sel_hi:[1,0]
	v_pk_mul_f32 v[4:5], v[4:5], v[170:171] op_sel_hi:[1,0]
	v_mov_b32_e32 v170, v208

; #define ATT_VREAD(dst, q_) do { const LAS char* vp_ = (const LAS char*)vb + (((q_) >> 1) * 32 + 16 * ((q_) & 1)) * VSTR; \
;         _Pragma("unroll") for (int d_ = 0; d_ < 4; ++d_) { dst[d_][0] = vtr(vp_ + voff[d_][0]); dst[d_][1] = vtr(vp_ + 8 * VSTR + voff[d_][1]); } } while (0)
;     ...
;         float mx = fmaxf(s0[0], s1[0]);
; #pragma unroll
;         for (int r = 1; r < 16; ++r) mx = fmaxf(mx, fmaxf(s0[r], s1[r]));
;         mx = fmaxf(mx, __shfl_xor(mx, 32));
;         const bool need = mx > mrun + 8.f;
;         if (__any(need)) { const float mnew = need ? mx : mrun, alpha = __builtin_amdgcn_exp2f(mrun - mnew); mrun = mnew; lrun *= alpha;
; #pragma unroll
;             for (int d = 0; d < 4; ++d)
; #pragma unroll
;                 for (int r = 0; r < 16; ++r) o[d][r] *= alpha; }
;     ...
;             if (wkb) { vb = sbb + KBUF + vlane; ATT_VREAD(vpre, 0); SM(wb0, wb1, b0, b1, pbb);
.LBB0_590:
	s_and_b64 vcc, exec, s[2:3]
	s_cbranch_vccnz .LBB0_594
	v_max_f32_e32 v156, v117, v117
	v_max_f32_e32 v157, v85, v85
	v_max_f32_e32 v156, v157, v156
	v_max_f32_e32 v157, v118, v118
	v_max_f32_e32 v158, v86, v86
	v_max_f32_e32 v157, v158, v157
	v_max_f32_e32 v158, v119, v119
	v_max_f32_e32 v159, v87, v87
	v_max3_f32 v156, v84, v116, v156
	v_max_f32_e32 v158, v159, v158
	v_max3_f32 v156, v156, v157, v158
	v_max_f32_e32 v157, v120, v120
	v_max_f32_e32 v158, v88, v88
	v_max_f32_e32 v157, v158, v157
	v_max_f32_e32 v158, v121, v121
	v_max_f32_e32 v159, v89, v89
	v_max_f32_e32 v158, v159, v158
	v_max3_f32 v156, v156, v157, v158
	v_max_f32_e32 v157, v122, v122
	v_max_f32_e32 v158, v90, v90
	v_max_f32_e32 v157, v158, v157
	v_max_f32_e32 v158, v123, v123
	v_max_f32_e32 v159, v91, v91
	v_max_f32_e32 v158, v159, v158
	v_max3_f32 v156, v156, v157, v158
	v_max_f32_e32 v157, v124, v124
	v_max_f32_e32 v158, v92, v92
	v_max_f32_e32 v157, v158, v157
	v_max_f32_e32 v158, v125, v125
	v_max_f32_e32 v159, v93, v93
	v_max_f32_e32 v158, v159, v158
	v_max3_f32 v156, v156, v157, v158
	v_max_f32_e32 v157, v126, v126
	v_max_f32_e32 v158, v94, v94
	v_max_f32_e32 v157, v158, v157
	v_max_f32_e32 v158, v127, v127
	v_max_f32_e32 v159, v95, v95
	v_max_f32_e32 v158, v159, v158
	v_max3_f32 v156, v156, v157, v158
	v_max_f32_e32 v157, v128, v128
	v_max_f32_e32 v158, v96, v96
	v_max_f32_e32 v157, v158, v157
	v_max_f32_e32 v158, v129, v129
	v_max_f32_e32 v159, v97, v97
	v_max_f32_e32 v158, v159, v158
	v_max3_f32 v156, v156, v157, v158
	v_max_f32_e32 v157, v130, v130
	v_max_f32_e32 v158, v98, v98
	v_max_f32_e32 v157, v158, v157
	v_max_f32_e32 v158, v131, v131
	v_max_f32_e32 v159, v99, v99
	v_max_f32_e32 v158, v159, v158
	v_max3_f32 v208, v156, v157, v158
	ds_read_b64_tr_b16 v[152:153], v200 offset:49152
	ds_read_b64_tr_b16 v[154:155], v201 offset:51200
	ds_read_b64_tr_b16 v[148:149], v202 offset:49152
	ds_read_b64_tr_b16 v[150:151], v203 offset:51200
	v_mov_b32_e32 v246, v208
	v_mov_b32_e32 v247, v208
	ds_read_b64_tr_b16 v[160:161], v204 offset:49152
	ds_read_b64_tr_b16 v[162:163], v205 offset:51200
	ds_read_b64_tr_b16 v[156:157], v206 offset:49152
	ds_read_b64_tr_b16 v[158:159], v207 offset:51200
	v_permlane32_swap_b32_e32 v246, v247
	v_max3_f32 v208, v208, v246, v247
	v_add_f32_e32 v209, 0x41000000, v170
	v_cmp_gt_f32_e32 vcc, v208, v209
	s_cbranch_vccz .LBB0_593
	s_nop 0
	v_cndmask_b32_e32 v208, v170, v208, vcc
	v_sub_f32_e32 v170, v170, v208
	v_exp_f32_e32 v170, v170
	s_nop 0
	v_mul_f32_e32 v167, v167, v170
	v_pk_mul_f32 v[66:67], v[66:67], v[170:171] op_sel_hi:[1,0]
	v_pk_mul_f32 v[64:65], v[64:65], v[170:171] op_sel_hi:[1,0]
	v_pk_mul_f32 v[62:63], v[62:63], v[170:171] op_sel_hi:[1,0]
	v_pk_mul_f32 v[60:61], v[60:61], v[170:171] op_sel_hi:[1,0]
	v_pk_mul_f32 v[58:59], v[58:59], v[170:171] op_sel_hi:[1,0]
	v_pk_mul_f32 v[56:57], v[56:57], v[170:171] op_sel_hi:[1,0]
	v_pk_mul_f32 v[54:55], v[54:55], v[170:171] op_sel_hi:[1,0]
	v_pk_mul_f32 v[52:53], v[52:53], v[170:171] op_sel_hi:[1,0]
	v_pk_mul_f32 v[50:51], v[50:51], v[170:171] op_sel_hi:[1,0]
	v_pk_mul_f32 v[48:49], v[48:49], v[170:171] op_sel_hi:[1,0]
	v_pk_mul_f32 v[46:47], v[46:47], v[170:171] op_sel_hi:[1,0]
	v_pk_mul_f32 v[44:45], v[44:45], v[170:171] op_sel_hi:[1,0]
	v_pk_mul_f32 v[42:43], v[42:43], v[170:171] op_sel_hi:[1,0]
	v_pk_mul_f32 v[40:41], v[40:41], v[170:171] op_sel_hi:[1,0]
	v_pk_mul_f32 v[38:39], v[38:39], v[170:171] op_sel_hi:[1,0]
	v_pk_mul_f32 v[36:37], v[36:37], v[170:171] op_sel_hi:[1,0]
	v_pk_mul_f32 v[34:35], v[34:35], v[170:171] op_sel_hi:[1,0]
	v_pk_mul_f32 v[32:33], v[32:33], v[170:171] op_sel_hi:[1,0]
	v_pk_mul_f32 v[30:31], v[30:31], v[170:171] op_sel_hi:[1,0]
	v_pk_mul_f32 v[28:29], v[28:29], v[170:171] op_sel_hi:[1,0]
	v_pk_mul_f32 v[26:27], v[26:27], v[170:171] op_sel_hi:[1,0]
	v_pk_mul_f32 v[24:25], v[24:25], v[170:171] op_sel_hi:[1,0]
	v_pk_mul_f32 v[22:23], v[22:23], v[170:171] op_sel_hi:[1,0]
	v_pk_mul_f32 v[20:21], v[20:21], v[170:171] op_sel_hi:[1,0]
	v_pk_mul_f32 v[18:19], v[18:19], v[170:171] op_sel_hi:[1,0]
	v_pk_mul_f32 v[16:17], v[16:17], v[170:171] op_sel_hi:[1,0]
	v_pk_mul_f32 v[14:15], v[14:15], v[170:171] op_sel_hi:[1,0]
	v_pk_mul_f32 v[12:13], v[12:13], v[170:171] op_sel_hi:[1,0]
	v_pk_mul_f32 v[10:11], v[10:11], v[170:171] op_sel_hi:[1,0]
	v_pk_mul_f32 v[8:9], v[8:9], v[170:171] op_sel_hi:[1,0]
	v_pk_mul_f32 v[6:7], v[6:7], v[170:171] op_sel_hi:[1,0]
	v_pk_mul_f32 v[4:5], v[4:5], v[170:171] op_sel_hi:[1,0]
	v_mov_b32_e32 v170, v208

; #define LAS __attribute__((address_space(3)))
; __device__ __forceinline__ int crow(int r, int hi) { return (r & 3) + 8 * (r >> 2) + 4 * hi; }
;     ...
;     auto QK = [&](const LAS unsigned char* sbase, f32x16& s0, f32x16& s1) {
;         const LAS unsigned char* kb = sbase + r32 * KSTR; const int kc0 = (koff >> 3) + hi;
; #pragma unroll
;         for (int r = 0; r < 16; ++r) { s0[r] = 0.f; s1[r] = 0.f; }
; #pragma unroll
;         for (int kh = 0; kh < NKS; kh += 4) {
;             bf16x8 ka[4][2];
; #pragma unroll
;             for (int ks = 0; ks < 4; ++ks) { const int ko = ((kc0 + 2 * (kh + ks)) ^ ksw) << 4; ka[ks][0] = *(const LAS bf16x8*)(kb + ko); ka[ks][1] = *(const LAS bf16x8*)(kb + 32 * KSTR + ko); }
;             __builtin_amdgcn_s_setprio(1);
; #pragma unroll
;             for (int ks = 0; ks < 4; ++ks) { s0 = __builtin_amdgcn_mfma_f32_32x32x16_bf16(ka[ks][0], qf[kh + ks], s0, 0, 0, 0); s1 = __builtin_amdgcn_mfma_f32_32x32x16_bf16(ka[ks][1], qf[kh + ks], s1, 0, 0, 0); }
;             __builtin_amdgcn_s_setprio(0);
;         }
;     };
;     auto SM = [&](unsigned w0, unsigned w1, f32x16& s0, f32x16& s1, bf16x8 (&pb)[2][2]) {
;         if (LAYER == 1) {
; #pragma unroll
;             for (int r = 0; r < 16; ++r) { const int kv = crow(r, hi); if (!((w0 >> kv) & 1u)) s0[r] = -1e30f; if (!((w1 >> kv) & 1u)) s1[r] = -1e30f; } }
;     ...
;             LAS unsigned char* const sa = lds + (p & 1) * STG2; LAS unsigned char* const sbb = sa + STAGEB;
;             const int ta = dual ? p : 2 * p, tb = dual ? p : 2 * p + 1;
;             const bool wka = active && !(dual && hsel) && ta <= my_last && !(xmode & 1), wkb = active && !(dual && !hsel) && tb < u.ntiles && tb <= my_last && !(xmode & 1);
;             f32x16 a0, a1, b0, b1; bf16x8 pba[2][2], pbb[2][2]; s16x4 vpre[4][2], va[4][2], vbb[4][2];
;             unsigned wa0 = 0xffffffffu, wa1 = 0xffffffffu, wb0 = 0xffffffffu, wb1 = 0xffffffffu;
;             if (LAYER == 1) { const v2u ma = *(const LAS v2u*)(sa + 2 * STAGEB + (32 * sb + r32) * 8), mb = *(const LAS v2u*)(sa + 2 * STAGEB + MSKB + (32 * sb + r32) * 8); wa0 = ma.x; wa1 = ma.y; wb0 = mb.x; wb1 = mb.y; }
;             if (wka) QK(sa, a0, a1);
.LBB0_2110:
	s_bitcmp1_b32 s4, 0
	s_cselect_b32 s0, 0x10400, 0
	s_add_i32 s0, s0, 0
	v_add_u32_e32 v82, s0, v172
	v_add_u32_e32 v83, 0x10200, v82
	s_waitcnt lgkmcnt(0)
	ds_read_b64 v[156:157], v83
	v_add_u32_e32 v83, s0, v173
	v_add_u32_e32 v84, s0, v171
	s_cmp_gt_i32 s85, s90
	v_add_u32_e32 v214, v83, v174
	v_add_u32_e32 v213, v83, v175
	v_add_u32_e32 v212, v83, v176
	v_add_u32_e32 v211, v83, v177
	v_add_u32_e32 v210, v83, v178
	v_add_u32_e32 v209, v83, v179
	v_add_u32_e32 v208, v83, v180
	v_add_u32_e32 v207, v83, v181
	v_add_u32_e32 v155, v84, v161
	v_add_u32_e32 v199, v84, v162
	v_add_u32_e32 v200, v84, v163
	v_add_u32_e32 v201, v84, v166
	v_add_u32_e32 v202, v84, v167
	v_add_u32_e32 v203, v84, v168
	v_add_u32_e32 v204, v84, v169
	v_add_u32_e32 v205, v84, v170
	s_cbranch_scc1 .LBB0_2114
	v_add_u32_e32 v82, 0x10000, v82
	ds_read_b64 v[240:241], v82
	ds_read_b128 v[82:85], v214
	ds_read_b128 v[98:101], v214 offset:8192
	ds_read_b128 v[102:105], v213
	ds_read_b128 v[134:137], v213 offset:8192
	ds_read_b128 v[106:109], v212
	ds_read_b128 v[138:141], v212 offset:8192
	ds_read_b128 v[110:113], v211
	ds_read_b128 v[216:219], v211 offset:8192
	s_setprio 1
	s_waitcnt lgkmcnt(0)
	v_mfma_f32_32x32x16_bf16 v[82:97], v[82:85], v[4:7], 0
	v_mfma_f32_32x32x16_bf16 v[82:97], v[102:105], v[8:11], v[82:97]
	v_mfma_f32_32x32x16_bf16 v[82:97], v[106:109], v[12:15], v[82:97]
	v_mfma_f32_32x32x16_bf16 v[82:97], v[110:113], v[114:117], v[82:97]
	s_setprio 0
	ds_read_b128 v[102:105], v210
	ds_read_b128 v[224:227], v210 offset:8192
	ds_read_b128 v[106:109], v209
	ds_read_b128 v[228:231], v209 offset:8192
	ds_read_b128 v[110:113], v208
	ds_read_b128 v[232:235], v208 offset:8192
	ds_read_b128 v[220:223], v207
	ds_read_b128 v[236:239], v207 offset:8192
	s_setprio 1
	s_waitcnt lgkmcnt(0)
	v_mfma_f32_32x32x16_bf16 v[82:97], v[102:105], v[118:121], v[82:97]
	v_mfma_f32_32x32x16_bf16 v[82:97], v[106:109], v[122:125], v[82:97]
	v_mfma_f32_32x32x16_bf16 v[82:97], v[110:113], v[126:129], v[82:97]
	v_mfma_f32_32x32x16_bf16 v[82:97], v[220:223], v[130:133], v[82:97]
	s_setprio 0
	v_mfma_f32_32x32x16_bf16 v[98:113], v[98:101], v[4:7], 0
	v_and_b32_e32 v215, v240, v182
	v_cmp_eq_u32_e64 s[20:21], 0, v215
	v_and_b32_e32 v221, v240, v183
	v_cmp_eq_u32_e64 s[10:11], 0, v221
	s_nop 5
	v_cndmask_b32_e64 v220, v82, v158, s[20:21]
	v_and_b32_e32 v82, v241, v183
	v_cmp_eq_u32_e64 s[66:67], 0, v82
	v_mfma_f32_32x32x16_bf16 v[98:113], v[134:137], v[8:11], v[98:113]
	v_and_b32_e32 v82, v240, v191
	v_cmp_eq_u32_e64 s[50:51], 0, v82
	v_and_b32_e32 v82, v241, v191
	v_cmp_eq_u32_e64 s[52:53], 0, v82
	v_and_b32_e32 v82, v240, v193
	v_cmp_eq_u32_e64 s[46:47], 0, v82
	v_and_b32_e32 v82, v241, v193
	v_mfma_f32_32x32x16_bf16 v[98:113], v[138:141], v[12:15], v[98:113]
	v_cmp_eq_u32_e64 s[48:49], 0, v82
	v_and_b32_e32 v82, v240, v194
	v_cmp_eq_u32_e64 s[40:41], 0, v82
	v_and_b32_e32 v82, v241, v194
	v_cmp_eq_u32_e64 s[42:43], 0, v82
	v_and_b32_e32 v82, v240, v195
	v_cmp_eq_u32_e64 s[36:37], 0, v82
	v_mfma_f32_32x32x16_bf16 v[98:113], v[216:219], v[114:117], v[98:113]
	v_and_b32_e32 v82, v241, v195
	v_cmp_eq_u32_e64 s[38:39], 0, v82
	v_and_b32_e32 v82, v240, v196
	v_cmp_eq_u32_e64 s[30:31], 0, v82
	v_and_b32_e32 v82, v241, v196
	v_cmp_eq_u32_e64 s[34:35], 0, v82
	v_and_b32_e32 v82, v240, v197
	v_mfma_f32_32x32x16_bf16 v[98:113], v[224:227], v[118:121], v[98:113]
	v_cndmask_b32_e64 v218, v83, v158, s[10:11]
	v_and_b32_e32 v83, v240, v184
	v_cmp_eq_u32_e64 s[26:27], 0, v82
	v_and_b32_e32 v82, v241, v197
	v_and_b32_e32 v242, v241, v184
	v_cmp_eq_u32_e64 s[18:19], 0, v83
	v_cmp_eq_u32_e64 s[28:29], 0, v82
	v_mfma_f32_32x32x16_bf16 v[98:113], v[228:231], v[122:125], v[98:113]
	v_and_b32_e32 v82, v240, v198
	v_and_b32_e32 v215, v240, v185
	v_cndmask_b32_e64 v222, v84, v158, s[18:19]
	v_and_b32_e32 v83, v241, v185
	v_and_b32_e32 v84, v240, v186
	v_cmp_eq_u32_e64 s[64:65], 0, v242
	v_cmp_eq_u32_e64 s[22:23], 0, v82
	v_mfma_f32_32x32x16_bf16 v[98:113], v[232:235], v[126:129], v[98:113]
	v_and_b32_e32 v82, v241, v198
	v_and_b32_e32 v223, v241, v182
	v_cmp_eq_u32_e64 s[8:9], 0, v215
	v_cmp_eq_u32_e64 s[16:17], 0, v84
	v_and_b32_e32 v84, v241, v187
	v_cmp_eq_u32_e64 s[62:63], 0, v83
	v_cmp_eq_u32_e64 s[24:25], 0, v82
	v_mfma_f32_32x32x16_bf16 v[98:113], v[236:239], v[130:133], v[98:113]
	v_max_f32_e32 v83, v218, v218
	v_cndmask_b32_e64 v217, v85, v158, s[8:9]
	v_and_b32_e32 v85, v241, v186
	v_cmp_eq_u32_e64 s[68:69], 0, v223
	v_cmp_eq_u32_e64 s[58:59], 0, v84
	v_max_f32_e32 v84, v222, v222
	v_and_b32_e32 v215, v240, v187
	s_nop 4
	v_cndmask_b32_e64 v230, v99, v158, s[66:67]
	v_cndmask_b32_e64 v229, v100, v158, s[64:65]
	v_max_f32_e32 v82, v230, v230
	v_cndmask_b32_e64 v228, v101, v158, s[62:63]
	v_max_f32_e32 v82, v83, v82
	v_max_f32_e32 v83, v229, v229
	v_cndmask_b32_e64 v231, v98, v158, s[68:69]
	v_cmp_eq_u32_e64 s[60:61], 0, v85
	v_max_f32_e32 v83, v84, v83
	v_max_f32_e32 v84, v228, v228
	v_max_f32_e32 v85, v217, v217
	v_cndmask_b32_e64 v221, v86, v158, s[16:17]
	v_cmp_eq_u32_e64 s[4:5], 0, v215
	v_cndmask_b32_e64 v227, v102, v158, s[60:61]
	v_max3_f32 v82, v220, v231, v82
	v_max_f32_e32 v84, v85, v84
	v_cndmask_b32_e64 v215, v87, v158, s[4:5]
	v_and_b32_e32 v86, v240, v188
	v_and_b32_e32 v87, v241, v188
; __device__ __forceinline__ int crow(int r, int hi) { return (r & 3) + 8 * (r >> 2) + 4 * hi; }
; #define ATT_VREAD(dst, q_) do { const LAS char* vp_ = (const LAS char*)vb + (((q_) >> 1) * 32 + 16 * ((q_) & 1)) * VSTR; \
;         _Pragma("unroll") for (int d_ = 0; d_ < 4; ++d_) { dst[d_][0] = vtr(vp_ + voff[d_][0]); dst[d_][1] = vtr(vp_ + 8 * VSTR + voff[d_][1]); } } while (0)
;     ...
;         if (LAYER == 1) {
; #pragma unroll
;             for (int r = 0; r < 16; ++r) { const int kv = crow(r, hi); if (!((w0 >> kv) & 1u)) s0[r] = -1e30f; if (!((w1 >> kv) & 1u)) s1[r] = -1e30f; } }
;         float mx = fmaxf(s0[0], s1[0]);
; #pragma unroll
;         for (int r = 1; r < 16; ++r) mx = fmaxf(mx, fmaxf(s0[r], s1[r]));
;         mx = fmaxf(mx, __shfl_xor(mx, 32));
;         const bool need = mx > mrun + 8.f;
;         if (__any(need)) { const float mnew = need ? mx : mrun, alpha = __builtin_amdgcn_exp2f(mrun - mnew); mrun = mnew; lrun *= alpha;
; #pragma unroll
;             for (int d = 0; d < 4; ++d)
; #pragma unroll
;                 for (int r = 0; r < 16; ++r) o[d][r] *= alpha; }
;     ...
;             if (wka) { vb = sa + KBUF + vlane; ATT_VREAD(vpre, 0); SM(wa0, wa1, a0, a1, pba);
	v_cndmask_b32_e64 v226, v103, v158, s[58:59]
	v_max3_f32 v82, v82, v83, v84
	v_max_f32_e32 v83, v227, v227
	v_max_f32_e32 v84, v221, v221
	v_and_b32_e32 v216, v240, v189
	v_cmp_eq_u32_e64 s[14:15], 0, v86
	v_and_b32_e32 v86, v241, v189
	v_cmp_eq_u32_e64 s[56:57], 0, v87
	v_max_f32_e32 v83, v84, v83
	v_max_f32_e32 v84, v226, v226
	v_max_f32_e32 v85, v215, v215
	v_cndmask_b32_e64 v219, v88, v158, s[14:15]
	v_cmp_eq_u32_e64 s[6:7], 0, v216
	v_cndmask_b32_e64 v225, v104, v158, s[56:57]
	v_cmp_eq_u32_e64 s[54:55], 0, v86
	v_max_f32_e32 v84, v85, v84
	v_cndmask_b32_e64 v216, v89, v158, s[6:7]
	v_and_b32_e32 v88, v240, v190
	v_and_b32_e32 v89, v241, v190
	v_cndmask_b32_e64 v223, v105, v158, s[54:55]
	v_max3_f32 v82, v82, v83, v84
	v_max_f32_e32 v83, v225, v225
	v_max_f32_e32 v84, v219, v219
	v_cmp_eq_u32_e64 s[12:13], 0, v88
	v_cmp_eq_u32_e64 s[44:45], 0, v89
	v_max_f32_e32 v83, v84, v83
	v_max_f32_e32 v84, v223, v223
	v_max_f32_e32 v85, v216, v216
	v_cndmask_b32_e64 v90, v90, v158, s[12:13]
	v_cndmask_b32_e64 v224, v106, v158, s[44:45]
	v_max_f32_e32 v84, v85, v84
	v_cndmask_b32_e64 v105, v91, v158, s[50:51]
	v_cndmask_b32_e64 v106, v107, v158, s[52:53]
	v_max3_f32 v82, v82, v83, v84
	v_max_f32_e32 v83, v224, v224
	v_max_f32_e32 v84, v90, v90
	v_max_f32_e32 v83, v84, v83
	v_max_f32_e32 v84, v106, v106
	v_max_f32_e32 v85, v105, v105
	v_cndmask_b32_e64 v103, v92, v158, s[46:47]
	v_cndmask_b32_e64 v104, v108, v158, s[48:49]
	v_max_f32_e32 v84, v85, v84
	v_cndmask_b32_e64 v101, v93, v158, s[40:41]
	v_cndmask_b32_e64 v102, v109, v158, s[42:43]
	v_max3_f32 v82, v82, v83, v84
	v_max_f32_e32 v83, v104, v104
	v_max_f32_e32 v84, v103, v103
	v_max_f32_e32 v83, v84, v83
	v_max_f32_e32 v84, v102, v102
	v_max_f32_e32 v85, v101, v101
	v_cndmask_b32_e64 v99, v94, v158, s[36:37]
	v_cndmask_b32_e64 v100, v110, v158, s[38:39]
	v_max_f32_e32 v84, v85, v84
	v_cndmask_b32_e64 v95, v95, v158, s[30:31]
	v_cndmask_b32_e64 v98, v111, v158, s[34:35]
	v_max3_f32 v82, v82, v83, v84
	v_max_f32_e32 v83, v100, v100
	v_max_f32_e32 v84, v99, v99
	v_max_f32_e32 v83, v84, v83
	v_max_f32_e32 v84, v98, v98
	v_max_f32_e32 v85, v95, v95
	v_cndmask_b32_e64 v93, v96, v158, s[26:27]
	v_cndmask_b32_e64 v94, v112, v158, s[28:29]
	v_max_f32_e32 v84, v85, v84
	v_cndmask_b32_e64 v91, v97, v158, s[22:23]
	v_cndmask_b32_e64 v92, v113, v158, s[24:25]
	v_max3_f32 v82, v82, v83, v84
	v_max_f32_e32 v83, v94, v94
	v_max_f32_e32 v84, v93, v93
	v_max_f32_e32 v83, v84, v83
	v_max_f32_e32 v84, v92, v92
	v_max_f32_e32 v85, v91, v91
	v_max_f32_e32 v84, v85, v84
	v_max3_f32 v96, v82, v83, v84
	ds_read_b64_tr_b16 v[138:139], v155 offset:16384
	ds_read_b64_tr_b16 v[140:141], v199 offset:18432
	ds_read_b64_tr_b16 v[134:135], v200 offset:16384
	ds_read_b64_tr_b16 v[136:137], v201 offset:18432
	v_mov_b32_e32 v246, v96
	v_mov_b32_e32 v247, v96
	ds_read_b64_tr_b16 v[86:87], v202 offset:16384
	ds_read_b64_tr_b16 v[88:89], v203 offset:18432
	ds_read_b64_tr_b16 v[82:83], v204 offset:16384
	ds_read_b64_tr_b16 v[84:85], v205 offset:18432
	v_permlane32_swap_b32_e32 v246, v247
	v_max3_f32 v96, v96, v246, v247
	v_add_f32_e32 v97, 0x41000000, v206
	v_cmp_gt_f32_e32 vcc, v96, v97
	s_cbranch_vccz .LBB0_2113
	s_nop 0
	v_cndmask_b32_e32 v97, v206, v96, vcc
	v_sub_f32_e32 v96, v206, v97
	v_exp_f32_e32 v96, v96
	v_mov_b32_e32 v206, v97
	v_mul_f32_e32 v192, v192, v96
	v_pk_mul_f32 v[80:81], v[80:81], v[96:97] op_sel_hi:[1,0]
	v_pk_mul_f32 v[78:79], v[78:79], v[96:97] op_sel_hi:[1,0]
	v_pk_mul_f32 v[76:77], v[76:77], v[96:97] op_sel_hi:[1,0]
	v_pk_mul_f32 v[74:75], v[74:75], v[96:97] op_sel_hi:[1,0]
	v_pk_mul_f32 v[72:73], v[72:73], v[96:97] op_sel_hi:[1,0]
	v_pk_mul_f32 v[70:71], v[70:71], v[96:97] op_sel_hi:[1,0]
	v_pk_mul_f32 v[68:69], v[68:69], v[96:97] op_sel_hi:[1,0]
	v_pk_mul_f32 v[66:67], v[66:67], v[96:97] op_sel_hi:[1,0]
	v_pk_mul_f32 v[64:65], v[64:65], v[96:97] op_sel_hi:[1,0]
	v_pk_mul_f32 v[62:63], v[62:63], v[96:97] op_sel_hi:[1,0]
	v_pk_mul_f32 v[60:61], v[60:61], v[96:97] op_sel_hi:[1,0]
	v_pk_mul_f32 v[58:59], v[58:59], v[96:97] op_sel_hi:[1,0]
	v_pk_mul_f32 v[56:57], v[56:57], v[96:97] op_sel_hi:[1,0]
	v_pk_mul_f32 v[54:55], v[54:55], v[96:97] op_sel_hi:[1,0]
	v_pk_mul_f32 v[52:53], v[52:53], v[96:97] op_sel_hi:[1,0]
	v_pk_mul_f32 v[50:51], v[50:51], v[96:97] op_sel_hi:[1,0]
	v_pk_mul_f32 v[48:49], v[48:49], v[96:97] op_sel_hi:[1,0]
	v_pk_mul_f32 v[46:47], v[46:47], v[96:97] op_sel_hi:[1,0]
	v_pk_mul_f32 v[44:45], v[44:45], v[96:97] op_sel_hi:[1,0]
	v_pk_mul_f32 v[42:43], v[42:43], v[96:97] op_sel_hi:[1,0]
	v_pk_mul_f32 v[40:41], v[40:41], v[96:97] op_sel_hi:[1,0]
	v_pk_mul_f32 v[38:39], v[38:39], v[96:97] op_sel_hi:[1,0]
	v_pk_mul_f32 v[36:37], v[36:37], v[96:97] op_sel_hi:[1,0]
	v_pk_mul_f32 v[34:35], v[34:35], v[96:97] op_sel_hi:[1,0]
	v_pk_mul_f32 v[32:33], v[32:33], v[96:97] op_sel_hi:[1,0]
	v_pk_mul_f32 v[30:31], v[30:31], v[96:97] op_sel_hi:[1,0]
	v_pk_mul_f32 v[28:29], v[28:29], v[96:97] op_sel_hi:[1,0]
	v_pk_mul_f32 v[26:27], v[26:27], v[96:97] op_sel_hi:[1,0]
	v_pk_mul_f32 v[24:25], v[24:25], v[96:97] op_sel_hi:[1,0]
	v_pk_mul_f32 v[22:23], v[22:23], v[96:97] op_sel_hi:[1,0]
	v_pk_mul_f32 v[20:21], v[20:21], v[96:97] op_sel_hi:[1,0]
	v_pk_mul_f32 v[18:19], v[18:19], v[96:97] op_sel_hi:[1,0]

; #define LAS __attribute__((address_space(3)))
; __device__ __forceinline__ int crow(int r, int hi) { return (r & 3) + 8 * (r >> 2) + 4 * hi; }
;     ...
;     auto QK = [&](const LAS unsigned char* sbase, f32x16& s0, f32x16& s1) {
;         const LAS unsigned char* kb = sbase + r32 * KSTR; const int kc0 = (koff >> 3) + hi;
; #pragma unroll
;         for (int r = 0; r < 16; ++r) { s0[r] = 0.f; s1[r] = 0.f; }
; #pragma unroll
;         for (int kh = 0; kh < NKS; kh += 4) {
;             bf16x8 ka[4][2];
; #pragma unroll
;             for (int ks = 0; ks < 4; ++ks) { const int ko = ((kc0 + 2 * (kh + ks)) ^ ksw) << 4; ka[ks][0] = *(const LAS bf16x8*)(kb + ko); ka[ks][1] = *(const LAS bf16x8*)(kb + 32 * KSTR + ko); }
;             __builtin_amdgcn_s_setprio(1);
; #pragma unroll
;             for (int ks = 0; ks < 4; ++ks) { s0 = __builtin_amdgcn_mfma_f32_32x32x16_bf16(ka[ks][0], qf[kh + ks], s0, 0, 0, 0); s1 = __builtin_amdgcn_mfma_f32_32x32x16_bf16(ka[ks][1], qf[kh + ks], s1, 0, 0, 0); }
;             __builtin_amdgcn_s_setprio(0);
;         }
;     };
;     auto SM = [&](unsigned w0, unsigned w1, f32x16& s0, f32x16& s1, bf16x8 (&pb)[2][2]) {
;         if (LAYER == 1) {
; #pragma unroll
;             for (int r = 0; r < 16; ++r) { const int kv = crow(r, hi); if (!((w0 >> kv) & 1u)) s0[r] = -1e30f; if (!((w1 >> kv) & 1u)) s1[r] = -1e30f; } }
;     ...
;             if (LAYER == 1) { if (wkb) QK(sbb, b0, b1); }
.LBB0_2114:
	s_cmp_ge_i32 s85, s90
	s_cbranch_scc1 .LBB0_2118
	ds_read_b128 v[82:85], v214 offset:32768
	ds_read_b128 v[98:101], v214 offset:40960
	ds_read_b128 v[102:105], v213 offset:32768
	ds_read_b128 v[134:137], v213 offset:40960
	ds_read_b128 v[106:109], v212 offset:32768
	ds_read_b128 v[138:141], v212 offset:40960
	ds_read_b128 v[110:113], v211 offset:32768
	ds_read_b128 v[214:217], v211 offset:40960
	s_setprio 1
	s_waitcnt lgkmcnt(0)
	v_mfma_f32_32x32x16_bf16 v[82:97], v[82:85], v[4:7], 0
	v_mfma_f32_32x32x16_bf16 v[82:97], v[102:105], v[8:11], v[82:97]
	v_mfma_f32_32x32x16_bf16 v[82:97], v[106:109], v[12:15], v[82:97]
	v_mfma_f32_32x32x16_bf16 v[82:97], v[110:113], v[114:117], v[82:97]
	s_setprio 0
	ds_read_b128 v[102:105], v210 offset:32768
	ds_read_b128 v[218:221], v210 offset:40960
	ds_read_b128 v[106:109], v209 offset:32768
	ds_read_b128 v[222:225], v209 offset:40960
	ds_read_b128 v[110:113], v208 offset:32768
	ds_read_b128 v[226:229], v208 offset:40960
	ds_read_b128 v[208:211], v207 offset:32768
	ds_read_b128 v[230:233], v207 offset:40960
	s_setprio 1
	s_waitcnt lgkmcnt(0)
	v_mfma_f32_32x32x16_bf16 v[82:97], v[102:105], v[118:121], v[82:97]
	v_mfma_f32_32x32x16_bf16 v[82:97], v[106:109], v[122:125], v[82:97]
	v_mfma_f32_32x32x16_bf16 v[82:97], v[110:113], v[126:129], v[82:97]
	v_mfma_f32_32x32x16_bf16 v[82:97], v[208:211], v[130:133], v[82:97]
	s_setprio 0
	v_mfma_f32_32x32x16_bf16 v[98:113], v[98:101], v[4:7], 0
	v_and_b32_e32 v207, v156, v182
	v_cmp_eq_u32_e64 s[20:21], 0, v207
	v_and_b32_e32 v208, v156, v183
	v_cmp_eq_u32_e64 s[10:11], 0, v208
	s_nop 5
	v_cndmask_b32_e64 v212, v82, v158, s[20:21]
	v_and_b32_e32 v82, v157, v183
	v_cmp_eq_u32_e64 s[66:67], 0, v82
	v_mfma_f32_32x32x16_bf16 v[98:113], v[134:137], v[8:11], v[98:113]
	v_and_b32_e32 v82, v156, v191
	v_cmp_eq_u32_e64 s[50:51], 0, v82
	v_and_b32_e32 v82, v157, v191
	v_cmp_eq_u32_e64 s[52:53], 0, v82
	v_and_b32_e32 v82, v156, v193
	v_cmp_eq_u32_e64 s[46:47], 0, v82
	v_and_b32_e32 v82, v157, v193
	v_mfma_f32_32x32x16_bf16 v[98:113], v[138:141], v[12:15], v[98:113]
	v_cmp_eq_u32_e64 s[48:49], 0, v82
	v_and_b32_e32 v82, v156, v194
	v_cmp_eq_u32_e64 s[40:41], 0, v82
	v_and_b32_e32 v82, v157, v194
	v_cmp_eq_u32_e64 s[42:43], 0, v82
	v_and_b32_e32 v82, v156, v195
	v_cmp_eq_u32_e64 s[36:37], 0, v82
	v_mfma_f32_32x32x16_bf16 v[98:113], v[214:217], v[114:117], v[98:113]
	v_and_b32_e32 v82, v157, v195
	v_cmp_eq_u32_e64 s[38:39], 0, v82
	v_and_b32_e32 v82, v156, v196
	v_cmp_eq_u32_e64 s[30:31], 0, v82
	v_and_b32_e32 v82, v157, v196
	v_cmp_eq_u32_e64 s[34:35], 0, v82
	v_and_b32_e32 v82, v156, v197
	v_mfma_f32_32x32x16_bf16 v[98:113], v[218:221], v[118:121], v[98:113]
	v_cndmask_b32_e64 v210, v83, v158, s[10:11]
	v_and_b32_e32 v83, v156, v184
	v_cmp_eq_u32_e64 s[26:27], 0, v82
	v_and_b32_e32 v82, v157, v197
	v_and_b32_e32 v215, v157, v184
	v_cmp_eq_u32_e64 s[18:19], 0, v83
	v_cmp_eq_u32_e64 s[28:29], 0, v82
	v_mfma_f32_32x32x16_bf16 v[98:113], v[222:225], v[122:125], v[98:113]
	v_and_b32_e32 v82, v156, v198
	v_and_b32_e32 v207, v156, v185
	v_cndmask_b32_e64 v214, v84, v158, s[18:19]
	v_and_b32_e32 v83, v157, v185
	v_and_b32_e32 v84, v156, v186
	v_cmp_eq_u32_e64 s[64:65], 0, v215
	v_cmp_eq_u32_e64 s[22:23], 0, v82
	v_mfma_f32_32x32x16_bf16 v[98:113], v[226:229], v[126:129], v[98:113]
	v_and_b32_e32 v82, v157, v198
	v_and_b32_e32 v234, v157, v182
	v_cmp_eq_u32_e64 s[8:9], 0, v207
	v_cmp_eq_u32_e64 s[16:17], 0, v84
	v_and_b32_e32 v84, v157, v187
	v_cmp_eq_u32_e64 s[62:63], 0, v83
	v_cmp_eq_u32_e64 s[24:25], 0, v82
	v_mfma_f32_32x32x16_bf16 v[98:113], v[230:233], v[130:133], v[98:113]
	v_max_f32_e32 v83, v210, v210
	v_cndmask_b32_e64 v209, v85, v158, s[8:9]
	v_and_b32_e32 v85, v157, v186
	v_cmp_eq_u32_e64 s[68:69], 0, v234
	v_cmp_eq_u32_e64 s[58:59], 0, v84
	v_max_f32_e32 v84, v214, v214
	v_and_b32_e32 v207, v156, v187
	s_nop 4
	v_cndmask_b32_e64 v222, v99, v158, s[66:67]
	v_cndmask_b32_e64 v221, v100, v158, s[64:65]
	v_max_f32_e32 v82, v222, v222
	v_cndmask_b32_e64 v220, v101, v158, s[62:63]
	v_max_f32_e32 v82, v83, v82
	v_max_f32_e32 v83, v221, v221
	v_cndmask_b32_e64 v223, v98, v158, s[68:69]
	v_cmp_eq_u32_e64 s[60:61], 0, v85
	v_max_f32_e32 v83, v84, v83
	v_max_f32_e32 v84, v220, v220
	v_max_f32_e32 v85, v209, v209
	v_cndmask_b32_e64 v213, v86, v158, s[16:17]
	v_cmp_eq_u32_e64 s[4:5], 0, v207
	v_cndmask_b32_e64 v219, v102, v158, s[60:61]
	v_max3_f32 v82, v212, v223, v82
	v_max_f32_e32 v84, v85, v84
	v_cndmask_b32_e64 v207, v87, v158, s[4:5]
	v_and_b32_e32 v86, v156, v188
	v_and_b32_e32 v87, v157, v188
	v_cndmask_b32_e64 v218, v103, v158, s[58:59]
	v_max3_f32 v82, v82, v83, v84
	v_max_f32_e32 v83, v219, v219
	v_max_f32_e32 v84, v213, v213
	v_and_b32_e32 v208, v156, v189
	v_cmp_eq_u32_e64 s[14:15], 0, v86
	v_and_b32_e32 v86, v157, v189
	v_cmp_eq_u32_e64 s[56:57], 0, v87
	v_max_f32_e32 v83, v84, v83
	v_max_f32_e32 v84, v218, v218
; __device__ __forceinline__ int crow(int r, int hi) { return (r & 3) + 8 * (r >> 2) + 4 * hi; }
; #define ATT_VREAD(dst, q_) do { const LAS char* vp_ = (const LAS char*)vb + (((q_) >> 1) * 32 + 16 * ((q_) & 1)) * VSTR; \
;         _Pragma("unroll") for (int d_ = 0; d_ < 4; ++d_) { dst[d_][0] = vtr(vp_ + voff[d_][0]); dst[d_][1] = vtr(vp_ + 8 * VSTR + voff[d_][1]); } } while (0)
;     ...
;         if (LAYER == 1) {
; #pragma unroll
;             for (int r = 0; r < 16; ++r) { const int kv = crow(r, hi); if (!((w0 >> kv) & 1u)) s0[r] = -1e30f; if (!((w1 >> kv) & 1u)) s1[r] = -1e30f; } }
;         float mx = fmaxf(s0[0], s1[0]);
; #pragma unroll
;         for (int r = 1; r < 16; ++r) mx = fmaxf(mx, fmaxf(s0[r], s1[r]));
;         mx = fmaxf(mx, __shfl_xor(mx, 32));
;         const bool need = mx > mrun + 8.f;
;         if (__any(need)) { const float mnew = need ? mx : mrun, alpha = __builtin_amdgcn_exp2f(mrun - mnew); mrun = mnew; lrun *= alpha;
; #pragma unroll
;             for (int d = 0; d < 4; ++d)
; #pragma unroll
;                 for (int r = 0; r < 16; ++r) o[d][r] *= alpha; }
;     ...
;             if (wkb) { vb = sbb + KBUF + vlane; ATT_VREAD(vpre, 0); SM(wb0, wb1, b0, b1, pbb);
	v_max_f32_e32 v85, v207, v207
	v_cndmask_b32_e64 v211, v88, v158, s[14:15]
	v_cmp_eq_u32_e64 s[6:7], 0, v208
	v_cndmask_b32_e64 v217, v104, v158, s[56:57]
	v_cmp_eq_u32_e64 s[54:55], 0, v86
	v_max_f32_e32 v84, v85, v84
	v_cndmask_b32_e64 v208, v89, v158, s[6:7]
	v_and_b32_e32 v88, v156, v190
	v_and_b32_e32 v89, v157, v190
	v_cndmask_b32_e64 v215, v105, v158, s[54:55]
	v_max3_f32 v82, v82, v83, v84
	v_max_f32_e32 v83, v217, v217
	v_max_f32_e32 v84, v211, v211
	v_cmp_eq_u32_e64 s[12:13], 0, v88
	v_cmp_eq_u32_e64 s[44:45], 0, v89
	v_max_f32_e32 v83, v84, v83
	v_max_f32_e32 v84, v215, v215
	v_max_f32_e32 v85, v208, v208
	v_cndmask_b32_e64 v90, v90, v158, s[12:13]
	v_cndmask_b32_e64 v216, v106, v158, s[44:45]
	v_max_f32_e32 v84, v85, v84
	v_cndmask_b32_e64 v105, v91, v158, s[50:51]
	v_cndmask_b32_e64 v106, v107, v158, s[52:53]
	v_max3_f32 v82, v82, v83, v84
	v_max_f32_e32 v83, v216, v216
	v_max_f32_e32 v84, v90, v90
	v_max_f32_e32 v83, v84, v83
	v_max_f32_e32 v84, v106, v106
	v_max_f32_e32 v85, v105, v105
	v_cndmask_b32_e64 v103, v92, v158, s[46:47]
	v_cndmask_b32_e64 v104, v108, v158, s[48:49]
	v_max_f32_e32 v84, v85, v84
	v_cndmask_b32_e64 v101, v93, v158, s[40:41]
	v_cndmask_b32_e64 v102, v109, v158, s[42:43]
	v_max3_f32 v82, v82, v83, v84
	v_max_f32_e32 v83, v104, v104
	v_max_f32_e32 v84, v103, v103
	v_max_f32_e32 v83, v84, v83
	v_max_f32_e32 v84, v102, v102
	v_max_f32_e32 v85, v101, v101
	v_cndmask_b32_e64 v99, v94, v158, s[36:37]
	v_cndmask_b32_e64 v100, v110, v158, s[38:39]
	v_max_f32_e32 v84, v85, v84
	v_cndmask_b32_e64 v95, v95, v158, s[30:31]
	v_cndmask_b32_e64 v98, v111, v158, s[34:35]
	v_max3_f32 v82, v82, v83, v84
	v_max_f32_e32 v83, v100, v100
	v_max_f32_e32 v84, v99, v99
	v_max_f32_e32 v83, v84, v83
	v_max_f32_e32 v84, v98, v98
	v_max_f32_e32 v85, v95, v95
	v_cndmask_b32_e64 v93, v96, v158, s[26:27]
	v_cndmask_b32_e64 v94, v112, v158, s[28:29]
	v_max_f32_e32 v84, v85, v84
	v_cndmask_b32_e64 v91, v97, v158, s[22:23]
	v_cndmask_b32_e64 v92, v113, v158, s[24:25]
	v_max3_f32 v82, v82, v83, v84
	v_max_f32_e32 v83, v94, v94
	v_max_f32_e32 v84, v93, v93
	v_max_f32_e32 v83, v84, v83
	v_max_f32_e32 v84, v92, v92
	v_max_f32_e32 v85, v91, v91
	v_max_f32_e32 v84, v85, v84
	v_max3_f32 v96, v82, v83, v84
	ds_read_b64_tr_b16 v[138:139], v155 offset:49152
	ds_read_b64_tr_b16 v[140:141], v199 offset:51200
	ds_read_b64_tr_b16 v[134:135], v200 offset:49152
	ds_read_b64_tr_b16 v[136:137], v201 offset:51200
	v_mov_b32_e32 v246, v96
	v_mov_b32_e32 v247, v96
	ds_read_b64_tr_b16 v[86:87], v202 offset:49152
	ds_read_b64_tr_b16 v[88:89], v203 offset:51200
	ds_read_b64_tr_b16 v[82:83], v204 offset:49152
	ds_read_b64_tr_b16 v[84:85], v205 offset:51200
	v_permlane32_swap_b32_e32 v246, v247
	v_max3_f32 v96, v96, v246, v247
	v_add_f32_e32 v97, 0x41000000, v206
	v_cmp_gt_f32_e32 vcc, v96, v97
	s_cbranch_vccz .LBB0_2117
	s_nop 0
	v_cndmask_b32_e32 v97, v206, v96, vcc
	v_sub_f32_e32 v96, v206, v97
	v_exp_f32_e32 v96, v96
	v_mov_b32_e32 v206, v97
	v_mul_f32_e32 v192, v192, v96
	v_pk_mul_f32 v[80:81], v[80:81], v[96:97] op_sel_hi:[1,0]
	v_pk_mul_f32 v[78:79], v[78:79], v[96:97] op_sel_hi:[1,0]
	v_pk_mul_f32 v[76:77], v[76:77], v[96:97] op_sel_hi:[1,0]
	v_pk_mul_f32 v[74:75], v[74:75], v[96:97] op_sel_hi:[1,0]
	v_pk_mul_f32 v[72:73], v[72:73], v[96:97] op_sel_hi:[1,0]
	v_pk_mul_f32 v[70:71], v[70:71], v[96:97] op_sel_hi:[1,0]
	v_pk_mul_f32 v[68:69], v[68:69], v[96:97] op_sel_hi:[1,0]
	v_pk_mul_f32 v[66:67], v[66:67], v[96:97] op_sel_hi:[1,0]
	v_pk_mul_f32 v[64:65], v[64:65], v[96:97] op_sel_hi:[1,0]
	v_pk_mul_f32 v[62:63], v[62:63], v[96:97] op_sel_hi:[1,0]
	v_pk_mul_f32 v[60:61], v[60:61], v[96:97] op_sel_hi:[1,0]
	v_pk_mul_f32 v[58:59], v[58:59], v[96:97] op_sel_hi:[1,0]
	v_pk_mul_f32 v[56:57], v[56:57], v[96:97] op_sel_hi:[1,0]
	v_pk_mul_f32 v[54:55], v[54:55], v[96:97] op_sel_hi:[1,0]
	v_pk_mul_f32 v[52:53], v[52:53], v[96:97] op_sel_hi:[1,0]
	v_pk_mul_f32 v[50:51], v[50:51], v[96:97] op_sel_hi:[1,0]
	v_pk_mul_f32 v[48:49], v[48:49], v[96:97] op_sel_hi:[1,0]
	v_pk_mul_f32 v[46:47], v[46:47], v[96:97] op_sel_hi:[1,0]
	v_pk_mul_f32 v[44:45], v[44:45], v[96:97] op_sel_hi:[1,0]
	v_pk_mul_f32 v[42:43], v[42:43], v[96:97] op_sel_hi:[1,0]
	v_pk_mul_f32 v[40:41], v[40:41], v[96:97] op_sel_hi:[1,0]
	v_pk_mul_f32 v[38:39], v[38:39], v[96:97] op_sel_hi:[1,0]
	v_pk_mul_f32 v[36:37], v[36:37], v[96:97] op_sel_hi:[1,0]
	v_pk_mul_f32 v[34:35], v[34:35], v[96:97] op_sel_hi:[1,0]
	v_pk_mul_f32 v[32:33], v[32:33], v[96:97] op_sel_hi:[1,0]
	v_pk_mul_f32 v[30:31], v[30:31], v[96:97] op_sel_hi:[1,0]
	v_pk_mul_f32 v[28:29], v[28:29], v[96:97] op_sel_hi:[1,0]
	v_pk_mul_f32 v[26:27], v[26:27], v[96:97] op_sel_hi:[1,0]
	v_pk_mul_f32 v[24:25], v[24:25], v[96:97] op_sel_hi:[1,0]
	v_pk_mul_f32 v[22:23], v[22:23], v[96:97] op_sel_hi:[1,0]
	v_pk_mul_f32 v[20:21], v[20:21], v[96:97] op_sel_hi:[1,0]
	v_pk_mul_f32 v[18:19], v[18:19], v[96:97] op_sel_hi:[1,0]

; #define ATT_VREAD(dst, q_) do { const LAS char* vp_ = (const LAS char*)vb + (((q_) >> 1) * 32 + 16 * ((q_) & 1)) * VSTR; \
;         _Pragma("unroll") for (int d_ = 0; d_ < 4; ++d_) { dst[d_][0] = vtr(vp_ + voff[d_][0]); dst[d_][1] = vtr(vp_ + 8 * VSTR + voff[d_][1]); } } while (0)
;     ...
;         float mx = fmaxf(s0[0], s1[0]);
; #pragma unroll
;         for (int r = 1; r < 16; ++r) mx = fmaxf(mx, fmaxf(s0[r], s1[r]));
;         mx = fmaxf(mx, __shfl_xor(mx, 32));
;         const bool need = mx > mrun + 8.f;
;         if (__any(need)) { const float mnew = need ? mx : mrun, alpha = __builtin_amdgcn_exp2f(mrun - mnew); mrun = mnew; lrun *= alpha;
; #pragma unroll
;             for (int d = 0; d < 4; ++d)
; #pragma unroll
;                 for (int r = 0; r < 16; ++r) o[d][r] *= alpha; }
;     ...
;             if (wka) { vb = sa + KBUF + vlane; ATT_VREAD(vpre, 0); SM(wa0, wa1, a0, a1, pba);
.LBB0_3320:
	v_add_u32_e32 v146, s45, v195
	s_and_b64 vcc, exec, s[4:5]
	v_add_u32_e32 v201, v146, v171
	v_add_u32_e32 v202, v146, v188
	v_add_u32_e32 v203, v146, v189
	v_add_u32_e32 v204, v146, v190
	v_add_u32_e32 v205, v146, v191
	v_add_u32_e32 v206, v146, v192
	v_add_u32_e32 v207, v146, v193
	v_add_u32_e32 v208, v146, v194
	s_cbranch_vccnz .LBB0_3324
	v_max_f32_e32 v154, v99, v99
	v_max_f32_e32 v155, v67, v67
	v_max_f32_e32 v154, v155, v154
	v_max_f32_e32 v155, v100, v100
	v_max_f32_e32 v156, v68, v68
	v_max_f32_e32 v155, v156, v155
	v_max_f32_e32 v156, v101, v101
	v_max_f32_e32 v157, v69, v69
	v_max3_f32 v154, v66, v98, v154
	v_max_f32_e32 v156, v157, v156
	v_max3_f32 v154, v154, v155, v156
	v_max_f32_e32 v155, v102, v102
	v_max_f32_e32 v156, v70, v70
	v_max_f32_e32 v155, v156, v155
	v_max_f32_e32 v156, v103, v103
	v_max_f32_e32 v157, v71, v71
	v_max_f32_e32 v156, v157, v156
	v_max3_f32 v154, v154, v155, v156
	v_max_f32_e32 v155, v104, v104
	v_max_f32_e32 v156, v72, v72
	v_max_f32_e32 v155, v156, v155
	v_max_f32_e32 v156, v105, v105
	v_max_f32_e32 v157, v73, v73
	v_max_f32_e32 v156, v157, v156
	v_max3_f32 v154, v154, v155, v156
	v_max_f32_e32 v155, v106, v106
	v_max_f32_e32 v156, v74, v74
	v_max_f32_e32 v155, v156, v155
	v_max_f32_e32 v156, v107, v107
	v_max_f32_e32 v157, v75, v75
	v_max_f32_e32 v156, v157, v156
	v_max3_f32 v154, v154, v155, v156
	v_max_f32_e32 v155, v108, v108
	v_max_f32_e32 v156, v76, v76
	v_max_f32_e32 v155, v156, v155
	v_max_f32_e32 v156, v109, v109
	v_max_f32_e32 v157, v77, v77
	v_max_f32_e32 v156, v157, v156
	v_max3_f32 v154, v154, v155, v156
	v_max_f32_e32 v155, v110, v110
	v_max_f32_e32 v156, v78, v78
	v_max_f32_e32 v155, v156, v155
	v_max_f32_e32 v156, v111, v111
	v_max_f32_e32 v157, v79, v79
	v_max_f32_e32 v156, v157, v156
	v_max3_f32 v154, v154, v155, v156
	v_max_f32_e32 v155, v112, v112
	v_max_f32_e32 v156, v80, v80
	v_max_f32_e32 v155, v156, v155
	v_max_f32_e32 v156, v113, v113
	v_max_f32_e32 v157, v81, v81
	v_max_f32_e32 v156, v157, v156
	v_max3_f32 v209, v154, v155, v156
	ds_read_b64_tr_b16 v[150:151], v201 offset:16384
	ds_read_b64_tr_b16 v[152:153], v202 offset:18432
	ds_read_b64_tr_b16 v[146:147], v203 offset:16384
	ds_read_b64_tr_b16 v[148:149], v204 offset:18432
	v_mov_b32_e32 v246, v209
	v_mov_b32_e32 v247, v209
	ds_read_b64_tr_b16 v[158:159], v205 offset:16384
	ds_read_b64_tr_b16 v[160:161], v206 offset:18432
	ds_read_b64_tr_b16 v[154:155], v207 offset:16384
	ds_read_b64_tr_b16 v[156:157], v208 offset:18432
	v_permlane32_swap_b32_e32 v246, v247
	v_max3_f32 v209, v209, v246, v247
	v_add_f32_e32 v210, 0x41000000, v170
	v_cmp_gt_f32_e32 vcc, v209, v210
	s_cbranch_vccz .LBB0_3323
	s_nop 0
	v_cndmask_b32_e32 v209, v170, v209, vcc
	v_sub_f32_e32 v170, v170, v209
	v_exp_f32_e32 v170, v170
	s_nop 0
	v_mul_f32_e32 v167, v167, v170
	v_pk_mul_f32 v[64:65], v[64:65], v[170:171] op_sel_hi:[1,0]
	v_pk_mul_f32 v[62:63], v[62:63], v[170:171] op_sel_hi:[1,0]
	v_pk_mul_f32 v[60:61], v[60:61], v[170:171] op_sel_hi:[1,0]
	v_pk_mul_f32 v[58:59], v[58:59], v[170:171] op_sel_hi:[1,0]
	v_pk_mul_f32 v[56:57], v[56:57], v[170:171] op_sel_hi:[1,0]
	v_pk_mul_f32 v[54:55], v[54:55], v[170:171] op_sel_hi:[1,0]
	v_pk_mul_f32 v[52:53], v[52:53], v[170:171] op_sel_hi:[1,0]
	v_pk_mul_f32 v[50:51], v[50:51], v[170:171] op_sel_hi:[1,0]
	v_pk_mul_f32 v[48:49], v[48:49], v[170:171] op_sel_hi:[1,0]
	v_pk_mul_f32 v[46:47], v[46:47], v[170:171] op_sel_hi:[1,0]
	v_pk_mul_f32 v[44:45], v[44:45], v[170:171] op_sel_hi:[1,0]
	v_pk_mul_f32 v[42:43], v[42:43], v[170:171] op_sel_hi:[1,0]
	v_pk_mul_f32 v[40:41], v[40:41], v[170:171] op_sel_hi:[1,0]
	v_pk_mul_f32 v[38:39], v[38:39], v[170:171] op_sel_hi:[1,0]
	v_pk_mul_f32 v[36:37], v[36:37], v[170:171] op_sel_hi:[1,0]
	v_pk_mul_f32 v[34:35], v[34:35], v[170:171] op_sel_hi:[1,0]
	v_pk_mul_f32 v[32:33], v[32:33], v[170:171] op_sel_hi:[1,0]
	v_pk_mul_f32 v[30:31], v[30:31], v[170:171] op_sel_hi:[1,0]
	v_pk_mul_f32 v[28:29], v[28:29], v[170:171] op_sel_hi:[1,0]
	v_pk_mul_f32 v[26:27], v[26:27], v[170:171] op_sel_hi:[1,0]
	v_pk_mul_f32 v[24:25], v[24:25], v[170:171] op_sel_hi:[1,0]
	v_pk_mul_f32 v[22:23], v[22:23], v[170:171] op_sel_hi:[1,0]
	v_pk_mul_f32 v[20:21], v[20:21], v[170:171] op_sel_hi:[1,0]
	v_pk_mul_f32 v[18:19], v[18:19], v[170:171] op_sel_hi:[1,0]
	v_pk_mul_f32 v[16:17], v[16:17], v[170:171] op_sel_hi:[1,0]
	v_pk_mul_f32 v[14:15], v[14:15], v[170:171] op_sel_hi:[1,0]
	v_pk_mul_f32 v[12:13], v[12:13], v[170:171] op_sel_hi:[1,0]
	v_pk_mul_f32 v[10:11], v[10:11], v[170:171] op_sel_hi:[1,0]
	v_pk_mul_f32 v[8:9], v[8:9], v[170:171] op_sel_hi:[1,0]
	v_pk_mul_f32 v[6:7], v[6:7], v[170:171] op_sel_hi:[1,0]
	v_pk_mul_f32 v[4:5], v[4:5], v[170:171] op_sel_hi:[1,0]
	v_pk_mul_f32 v[2:3], v[2:3], v[170:171] op_sel_hi:[1,0]
	v_mov_b32_e32 v170, v209

; #define ATT_VREAD(dst, q_) do { const LAS char* vp_ = (const LAS char*)vb + (((q_) >> 1) * 32 + 16 * ((q_) & 1)) * VSTR; \
;         _Pragma("unroll") for (int d_ = 0; d_ < 4; ++d_) { dst[d_][0] = vtr(vp_ + voff[d_][0]); dst[d_][1] = vtr(vp_ + 8 * VSTR + voff[d_][1]); } } while (0)
;     ...
;         float mx = fmaxf(s0[0], s1[0]);
; #pragma unroll
;         for (int r = 1; r < 16; ++r) mx = fmaxf(mx, fmaxf(s0[r], s1[r]));
;         mx = fmaxf(mx, __shfl_xor(mx, 32));
;         const bool need = mx > mrun + 8.f;
;         if (__any(need)) { const float mnew = need ? mx : mrun, alpha = __builtin_amdgcn_exp2f(mrun - mnew); mrun = mnew; lrun *= alpha;
; #pragma unroll
;             for (int d = 0; d < 4; ++d)
; #pragma unroll
;                 for (int r = 0; r < 16; ++r) o[d][r] *= alpha; }
;     ...
;             if (wkb) { vb = sbb + KBUF + vlane; ATT_VREAD(vpre, 0); SM(wb0, wb1, b0, b1, pbb);
.LBB0_3324:
	s_and_b64 vcc, exec, s[2:3]
	s_cbranch_vccnz .LBB0_3328
	v_max_f32_e32 v154, v115, v115
	v_max_f32_e32 v155, v83, v83
	v_max_f32_e32 v154, v155, v154
	v_max_f32_e32 v155, v116, v116
	v_max_f32_e32 v156, v84, v84
	v_max_f32_e32 v155, v156, v155
	v_max_f32_e32 v156, v117, v117
	v_max_f32_e32 v157, v85, v85
	v_max3_f32 v154, v82, v114, v154
	v_max_f32_e32 v156, v157, v156
	v_max3_f32 v154, v154, v155, v156
	v_max_f32_e32 v155, v118, v118
	v_max_f32_e32 v156, v86, v86
	v_max_f32_e32 v155, v156, v155
	v_max_f32_e32 v156, v119, v119
	v_max_f32_e32 v157, v87, v87
	v_max_f32_e32 v156, v157, v156
	v_max3_f32 v154, v154, v155, v156
	v_max_f32_e32 v155, v120, v120
	v_max_f32_e32 v156, v88, v88
	v_max_f32_e32 v155, v156, v155
	v_max_f32_e32 v156, v121, v121
	v_max_f32_e32 v157, v89, v89
	v_max_f32_e32 v156, v157, v156
	v_max3_f32 v154, v154, v155, v156
	v_max_f32_e32 v155, v122, v122
	v_max_f32_e32 v156, v90, v90
	v_max_f32_e32 v155, v156, v155
	v_max_f32_e32 v156, v123, v123
	v_max_f32_e32 v157, v91, v91
	v_max_f32_e32 v156, v157, v156
	v_max3_f32 v154, v154, v155, v156
	v_max_f32_e32 v155, v124, v124
	v_max_f32_e32 v156, v92, v92
	v_max_f32_e32 v155, v156, v155
	v_max_f32_e32 v156, v125, v125
	v_max_f32_e32 v157, v93, v93
	v_max_f32_e32 v156, v157, v156
	v_max3_f32 v154, v154, v155, v156
	v_max_f32_e32 v155, v126, v126
	v_max_f32_e32 v156, v94, v94
	v_max_f32_e32 v155, v156, v155
	v_max_f32_e32 v156, v127, v127
	v_max_f32_e32 v157, v95, v95
	v_max_f32_e32 v156, v157, v156
	v_max3_f32 v154, v154, v155, v156
	v_max_f32_e32 v155, v128, v128
	v_max_f32_e32 v156, v96, v96
	v_max_f32_e32 v155, v156, v155
	v_max_f32_e32 v156, v129, v129
	v_max_f32_e32 v157, v97, v97
	v_max_f32_e32 v156, v157, v156
	v_max3_f32 v209, v154, v155, v156
	ds_read_b64_tr_b16 v[150:151], v201 offset:49152
	ds_read_b64_tr_b16 v[152:153], v202 offset:51200
	ds_read_b64_tr_b16 v[146:147], v203 offset:49152
	ds_read_b64_tr_b16 v[148:149], v204 offset:51200
	v_mov_b32_e32 v246, v209
	v_mov_b32_e32 v247, v209
	ds_read_b64_tr_b16 v[158:159], v205 offset:49152
	ds_read_b64_tr_b16 v[160:161], v206 offset:51200
	ds_read_b64_tr_b16 v[154:155], v207 offset:49152
	ds_read_b64_tr_b16 v[156:157], v208 offset:51200
	v_permlane32_swap_b32_e32 v246, v247
	v_max3_f32 v209, v209, v246, v247
	v_add_f32_e32 v210, 0x41000000, v170
	v_cmp_gt_f32_e32 vcc, v209, v210
	s_cbranch_vccz .LBB0_3327
	s_nop 0
	v_cndmask_b32_e32 v209, v170, v209, vcc
	v_sub_f32_e32 v170, v170, v209
	v_exp_f32_e32 v170, v170
	s_nop 0
	v_mul_f32_e32 v167, v167, v170
	v_pk_mul_f32 v[64:65], v[64:65], v[170:171] op_sel_hi:[1,0]
	v_pk_mul_f32 v[62:63], v[62:63], v[170:171] op_sel_hi:[1,0]
	v_pk_mul_f32 v[60:61], v[60:61], v[170:171] op_sel_hi:[1,0]
	v_pk_mul_f32 v[58:59], v[58:59], v[170:171] op_sel_hi:[1,0]
	v_pk_mul_f32 v[56:57], v[56:57], v[170:171] op_sel_hi:[1,0]
	v_pk_mul_f32 v[54:55], v[54:55], v[170:171] op_sel_hi:[1,0]
	v_pk_mul_f32 v[52:53], v[52:53], v[170:171] op_sel_hi:[1,0]
	v_pk_mul_f32 v[50:51], v[50:51], v[170:171] op_sel_hi:[1,0]
	v_pk_mul_f32 v[48:49], v[48:49], v[170:171] op_sel_hi:[1,0]
	v_pk_mul_f32 v[46:47], v[46:47], v[170:171] op_sel_hi:[1,0]
	v_pk_mul_f32 v[44:45], v[44:45], v[170:171] op_sel_hi:[1,0]
	v_pk_mul_f32 v[42:43], v[42:43], v[170:171] op_sel_hi:[1,0]
	v_pk_mul_f32 v[40:41], v[40:41], v[170:171] op_sel_hi:[1,0]
	v_pk_mul_f32 v[38:39], v[38:39], v[170:171] op_sel_hi:[1,0]
	v_pk_mul_f32 v[36:37], v[36:37], v[170:171] op_sel_hi:[1,0]
	v_pk_mul_f32 v[34:35], v[34:35], v[170:171] op_sel_hi:[1,0]
	v_pk_mul_f32 v[32:33], v[32:33], v[170:171] op_sel_hi:[1,0]
	v_pk_mul_f32 v[30:31], v[30:31], v[170:171] op_sel_hi:[1,0]
	v_pk_mul_f32 v[28:29], v[28:29], v[170:171] op_sel_hi:[1,0]
	v_pk_mul_f32 v[26:27], v[26:27], v[170:171] op_sel_hi:[1,0]
	v_pk_mul_f32 v[24:25], v[24:25], v[170:171] op_sel_hi:[1,0]
	v_pk_mul_f32 v[22:23], v[22:23], v[170:171] op_sel_hi:[1,0]
	v_pk_mul_f32 v[20:21], v[20:21], v[170:171] op_sel_hi:[1,0]
	v_pk_mul_f32 v[18:19], v[18:19], v[170:171] op_sel_hi:[1,0]
	v_pk_mul_f32 v[16:17], v[16:17], v[170:171] op_sel_hi:[1,0]
	v_pk_mul_f32 v[14:15], v[14:15], v[170:171] op_sel_hi:[1,0]
	v_pk_mul_f32 v[12:13], v[12:13], v[170:171] op_sel_hi:[1,0]
	v_pk_mul_f32 v[10:11], v[10:11], v[170:171] op_sel_hi:[1,0]
	v_pk_mul_f32 v[8:9], v[8:9], v[170:171] op_sel_hi:[1,0]
	v_pk_mul_f32 v[6:7], v[6:7], v[170:171] op_sel_hi:[1,0]
	v_pk_mul_f32 v[4:5], v[4:5], v[170:171] op_sel_hi:[1,0]
	v_pk_mul_f32 v[2:3], v[2:3], v[170:171] op_sel_hi:[1,0]
	v_mov_b32_e32 v170, v209
